# static s_setprio 1 for waves 4-7 during dil_attn and both gla_scan passes (reset at phase end)
# speedup vs baseline: 1.0053x; 1.0053x over previous
.LBB0_18:
	s_setprio 0
	v_readlane_b32 s1, v249, 12
	s_nop 0
	v_writelane_b32 v249, s61, 51
	s_add_i32 s1, s1, 1
	v_readlane_b32 s0, v249, 50
	s_cmp_ge_i32 s1, s41
	s_nop 0
	v_writelane_b32 v249, s0, 49
	s_mov_b32 s0, s12
	v_writelane_b32 v249, s0, 48
	v_writelane_b32 v249, s63, 47
	v_writelane_b32 v249, s62, 46
	s_nop 0
	v_readlane_b32 s2, v249, 44
	v_readlane_b32 s3, v249, 45
	s_nop 0
	v_writelane_b32 v249, s2, 42
	s_nop 1
	v_writelane_b32 v249, s3, 43
	v_writelane_b32 v249, s56, 41
	v_writelane_b32 v249, s74, 40
	v_readlane_b32 s48, v253, 58
	v_readlane_b32 s0, v249, 38
	v_readlane_b32 s49, v253, 59
	v_readlane_b32 s50, v253, 60
	v_writelane_b32 v249, s0, 37
	s_mov_b32 s0, s14
	v_writelane_b32 v249, s0, 36
	v_writelane_b32 v249, s72, 35
	v_readlane_b32 s51, v253, 61
	v_readlane_b32 s0, v249, 33
	v_readlane_b32 s52, v253, 62
	v_readlane_b32 s53, v253, 63
	v_writelane_b32 v249, s0, 32
	s_nop 0
	v_readlane_b32 s0, v249, 30
	s_nop 1
	v_writelane_b32 v249, s0, 29
	v_writelane_b32 v249, s73, 28
	s_nop 0
	v_readlane_b32 s0, v249, 26
	s_nop 1
	v_writelane_b32 v249, s0, 25
	v_writelane_b32 v249, s75, 24
	v_writelane_b32 v249, s76, 23
	s_nop 0
	v_readlane_b32 s0, v249, 21
	s_nop 1
	v_writelane_b32 v249, s0, 20
	s_nop 0
	v_readlane_b32 s0, v249, 18
	s_nop 1
	v_writelane_b32 v249, s0, 17
	v_writelane_b32 v249, s16, 15
	s_nop 1
	v_writelane_b32 v249, s17, 16
	v_writelane_b32 v249, s18, 13
	s_nop 1
	v_writelane_b32 v249, s19, 14
	s_nop 0
	v_readlane_b32 s64, v249, 10
	v_readlane_b32 s54, v249, 0
	v_readlane_b32 s55, v249, 1
	v_readlane_b32 s58, v249, 4
	v_readlane_b32 s59, v249, 5
	v_readlane_b32 s60, v249, 6
	v_readlane_b32 s61, v249, 7
	v_readlane_b32 s62, v249, 8
	v_readlane_b32 s63, v249, 9
	v_readlane_b32 s65, v249, 11
	v_readlane_b32 s56, v249, 2
	v_readlane_b32 s57, v249, 3
	s_cbranch_scc0 .LBB0_19
	s_getpc_b64 s[98:99]

.LBB0_93:
	v_readlane_b32 s0, v249, 56
	s_mov_b64 s[2:3], -1
	s_cmp_lt_i32 s0, 12
	s_mov_b64 s[0:1], 0
	s_cbranch_scc1 .LBB0_304
	v_readlane_b32 s0, v249, 56
	s_cmp_gt_i32 s0, 12
	s_cbranch_scc0 .LBB0_282
	s_cmp_gt_i32 s0, 20
	s_cbranch_scc0 .LBB0_283
	s_cmp_eq_u32 s0, 21
	s_mov_b64 s[0:1], -1
	s_cbranch_scc0 .LBB0_285
	v_writelane_b32 v248, s6, 5
	v_readlane_b32 s0, v251, 55
	v_readlane_b32 s1, v251, 56
	v_writelane_b32 v248, s7, 6
	v_writelane_b32 v249, s48, 59
	s_movk_i32 s2, 0x100
	v_writelane_b32 v248, s94, 1
	v_mov_b32_e32 v176, v179
	s_andn2_b64 vcc, exec, s[0:1]
	v_writelane_b32 v249, s49, 60
	v_writelane_b32 v248, s95, 2
	s_cbranch_vccnz .LBB0_284
	v_readfirstlane_b32 s98, v179
	s_nop 3
	s_lshr_b32 s98, s98, 8
	s_cmp_eq_u32 s98, 0
	s_cbranch_scc1 .Lprio_98
	s_setprio 1
.Lprio_98:
	v_readlane_b32 s0, v249, 59
	v_readlane_b32 s1, v249, 60
	s_lshl_b32 s0, s0, 2
	v_writelane_b32 v248, s0, 7
	v_cmp_gt_i32_e64 s[0:1], s2, v176
	v_bfe_u32 v2, v176, 5, 1
	v_lshrrev_b32_e32 v0, 1, v176
	v_writelane_b32 v248, s0, 8
	v_lshlrev_b32_e32 v1, 1, v176
	v_ashrrev_i32_e32 v3, 5, v176
	v_writelane_b32 v248, s1, 9
	v_cmp_eq_u32_e64 s[0:1], 0, v2
	v_and_b32_e32 v0, 4, v0
	v_and_b32_e32 v1, 8, v1
	v_and_b32_e32 v110, -2, v3
	v_and_b32_e32 v3, 19, v176
	v_cmp_lt_i32_e32 vcc, v210, v204
	v_writelane_b32 v249, s0, 63
	v_or3_b32 v112, v1, v3, v0
	v_cndmask_b32_e32 v1, v203, v210, vcc
	v_writelane_b32 v248, s1, 0
	v_readlane_b32 s0, v253, 53
	v_lshlrev_b32_e32 v100, 3, v2
	v_lshlrev_b32_e32 v114, 2, v1
	v_mov_b32_e32 v101, v177
	v_readlane_b32 s1, v253, 54
	v_add_u32_e32 v1, 0xffffffa0, v176
	s_movk_i32 s2, 0x81
	v_lshl_add_u64 v[104:105], s[0:1], 0, v[100:101]
	v_cmp_gt_u32_e64 s[0:1], s2, v1
	v_and_b32_e32 v103, 31, v176
	v_or_b32_e32 v0, 0xffffffc0, v100
	v_writelane_b32 v249, s0, 61
	v_sub_u32_e32 v1, v0, v103
	v_add_u32_e32 v3, 64, v1
	v_writelane_b32 v249, s1, 62
	v_readlane_b32 s0, v253, 47
	v_readlane_b32 s1, v253, 48
	v_cmp_gt_u32_e64 s[4:5], s2, v3
	v_lshl_add_u32 v102, v2, 4, 0
	v_lshl_add_u64 v[106:107], v[176:177], 2, s[0:1]
	v_readlane_b32 s0, v253, 43
	v_writelane_b32 v249, s4, 26
	s_movk_i32 s1, 0x41
	v_lshl_add_u32 v117, v1, 2, s0
	v_or_b32_e32 v1, 0xffffffc1, v100
	v_sub_u32_e32 v3, v1, v103
	v_add_u32_e32 v4, 64, v3
	v_lshl_add_u32 v118, v3, 2, s0
	v_or_b32_e32 v3, 0xffffffc2, v100
	v_writelane_b32 v249, s5, 27
	v_cmp_gt_u32_e64 s[4:5], s2, v4
	v_sub_u32_e32 v4, v3, v103
	v_add_u32_e32 v5, 64, v4
	v_writelane_b32 v249, s4, 21
	v_lshl_add_u32 v119, v4, 2, s0
	v_or_b32_e32 v4, 0xffffffc3, v100
	v_writelane_b32 v249, s5, 22
	v_cmp_gt_u32_e64 s[4:5], s2, v5
	v_sub_u32_e32 v5, v4, v103
	v_add_u32_e32 v6, 64, v5
	v_writelane_b32 v249, s4, 18
	v_lshl_add_u32 v120, v5, 2, s0
	v_or_b32_e32 v5, 0xffffffc4, v100
	v_writelane_b32 v249, s5, 19
	v_cmp_gt_u32_e64 s[4:5], s2, v6
	v_sub_u32_e32 v6, v5, v103
	v_add_u32_e32 v7, 64, v6
	v_writelane_b32 v249, s4, 30
	v_lshl_add_u32 v121, v6, 2, s0
	v_or_b32_e32 v6, 0xffffffc5, v100
	v_writelane_b32 v249, s5, 31
	v_cmp_gt_u32_e64 s[4:5], s2, v7
	v_sub_u32_e32 v7, v6, v103
	v_add_u32_e32 v8, 64, v7
	v_writelane_b32 v249, s4, 38
	v_lshl_add_u32 v122, v7, 2, s0
	v_or_b32_e32 v7, 0xffffffc6, v100
	v_writelane_b32 v249, s5, 39
	v_cmp_gt_u32_e64 s[4:5], s2, v8
	v_sub_u32_e32 v8, v7, v103
	v_add_u32_e32 v9, 64, v8
	v_lshl_add_u32 v123, v8, 2, s0
	v_or_b32_e32 v8, 0xffffffc7, v100
	v_cmp_gt_u32_e64 s[56:57], s2, v9
	v_sub_u32_e32 v9, v8, v103
	v_add_u32_e32 v10, 64, v9
	v_lshl_add_u32 v124, v9, 2, s0
	v_sub_u32_e32 v9, 16, v103
	v_add_u32_e32 v0, v0, v9
	v_cmp_gt_u32_e64 s[58:59], s2, v10
	v_add_u32_e32 v10, 64, v0
	v_lshl_add_u32 v125, v0, 2, s0
	v_add_u32_e32 v0, v1, v9
	v_add_u32_e32 v1, 64, v0
	v_lshl_add_u32 v126, v0, 2, s0
	v_add_u32_e32 v0, v3, v9
	v_cmp_gt_u32_e64 s[62:63], s2, v1
	v_add_u32_e32 v1, 64, v0
	v_lshl_add_u32 v127, v0, 2, s0
	v_add_u32_e32 v0, v4, v9
	v_cmp_gt_u32_e64 s[64:65], s2, v1
	v_add_u32_e32 v1, 64, v0
	v_lshl_add_u32 v128, v0, 2, s0
	v_add_u32_e32 v0, v5, v9
	v_cmp_gt_u32_e64 s[66:67], s2, v1
	v_add_u32_e32 v1, 64, v0
	v_lshl_add_u32 v129, v0, 2, s0
	v_add_u32_e32 v0, v6, v9
	v_cmp_gt_u32_e64 s[68:69], s2, v1
	v_add_u32_e32 v1, 64, v0
	v_lshl_add_u32 v130, v0, 2, s0
	v_add_u32_e32 v0, v7, v9
	v_cmp_gt_u32_e64 s[70:71], s2, v1
	v_add_u32_e32 v1, 64, v0
	v_lshl_add_u32 v131, v0, 2, s0
	v_add_u32_e32 v0, v8, v9
	v_cmp_gt_u32_e64 s[72:73], s2, v1
	v_add_u32_e32 v1, 64, v0
	v_lshl_add_u32 v132, v0, 2, s0
	v_or_b32_e32 v0, 0xffffffe0, v100
	v_cmp_gt_u32_e64 s[74:75], s2, v1
	v_sub_u32_e32 v1, v0, v103
	v_lshl_add_u32 v133, v1, 2, s0
	v_or_b32_e32 v1, 0xffffffe1, v100
	v_sub_u32_e32 v3, v1, v103
	v_lshl_add_u32 v134, v3, 2, s0
	v_or_b32_e32 v3, 0xffffffe2, v100
	v_sub_u32_e32 v4, v3, v103
	v_lshl_add_u32 v135, v4, 2, s0
	v_or_b32_e32 v4, 0xffffffe3, v100
	v_sub_u32_e32 v5, v4, v103
	v_lshl_add_u32 v136, v5, 2, s0
	v_or_b32_e32 v5, 0xffffffe4, v100
	v_sub_u32_e32 v6, v5, v103
	v_lshl_add_u32 v137, v6, 2, s0
	v_or_b32_e32 v6, 0xffffffe5, v100
	v_sub_u32_e32 v7, v6, v103
	v_lshl_add_u32 v138, v7, 2, s0
	v_or_b32_e32 v7, 0xffffffe6, v100
	v_sub_u32_e32 v8, v7, v103
	v_lshl_add_u32 v139, v8, 2, s0
	v_or_b32_e32 v8, 0xffffffe7, v100
	v_cmp_gt_u32_e64 s[60:61], s2, v10
	v_sub_u32_e32 v10, v8, v103
	v_lshl_add_u32 v140, v10, 2, s0
	v_lshlrev_b32_e32 v10, 2, v9
	v_add_u32_e32 v11, s0, v10
	v_lshl_add_u32 v141, v0, 2, v11
	v_sub_u32_e32 v0, v100, v103
	v_lshl_add_u32 v149, v0, 2, s0
	v_or_b32_e32 v0, 1, v100
	v_sub_u32_e32 v0, v0, v103
	v_lshl_add_u32 v150, v0, 2, s0
	v_or_b32_e32 v0, 2, v100
	v_sub_u32_e32 v0, v0, v103
	v_lshl_add_u32 v151, v0, 2, s0
	v_or_b32_e32 v0, 3, v100
	v_sub_u32_e32 v0, v0, v103
	v_lshl_add_u32 v152, v0, 2, s0
	v_or_b32_e32 v0, 4, v100
	v_sub_u32_e32 v0, v0, v103
	v_lshl_add_u32 v153, v0, 2, s0
	v_or_b32_e32 v0, 5, v100
	v_sub_u32_e32 v0, v0, v103
	v_lshl_add_u32 v154, v0, 2, s0
	v_or_b32_e32 v0, 6, v100
	v_sub_u32_e32 v0, v0, v103
	v_lshl_add_u32 v155, v0, 2, s0
	v_or_b32_e32 v0, 7, v100
	v_sub_u32_e32 v0, v0, v103
	v_lshl_add_u32 v156, v0, 2, s0
	v_lshlrev_b32_e32 v0, 5, v2
	v_add3_u32 v157, s0, v0, v10
	v_add_u32_e32 v158, v11, v0
	v_or_b32_e32 v0, 32, v100
	v_sub_u32_e32 v0, v0, v103
	v_lshl_add_u32 v159, v0, 2, s0
	v_or_b32_e32 v0, 33, v100
	v_sub_u32_e32 v0, v0, v103
	v_lshl_add_u32 v160, v0, 2, s0
	v_or_b32_e32 v0, 34, v100
	v_sub_u32_e32 v0, v0, v103
	v_lshl_add_u32 v161, v0, 2, s0
	v_or_b32_e32 v0, 35, v100
	v_sub_u32_e32 v0, v0, v103
	v_lshl_add_u32 v162, v0, 2, s0
	v_or_b32_e32 v0, 36, v100
	v_sub_u32_e32 v0, v0, v103
	v_lshl_add_u32 v163, v0, 2, s0
	v_or_b32_e32 v0, 37, v100
	v_sub_u32_e32 v0, v0, v103
	v_lshl_add_u32 v164, v0, 2, s0
	v_or_b32_e32 v0, 38, v100
	v_sub_u32_e32 v0, v0, v103
	v_lshl_add_u32 v165, v0, 2, s0
	v_or_b32_e32 v0, 39, v100
	v_sub_u32_e32 v0, v0, v103
	v_lshl_add_u32 v166, v0, 2, s0
	v_or_b32_e32 v0, 64, v100
	v_lshl_add_u32 v142, v1, 2, v11
	v_sub_u32_e32 v1, v0, v103
	v_cmp_gt_u32_e64 s[76:77], s1, v1
	v_lshl_add_u32 v167, v1, 2, s0
	v_or_b32_e32 v1, 0x41, v100
	v_sub_u32_e32 v2, v1, v103
	v_cmp_gt_u32_e64 s[78:79], s1, v2
	v_lshl_add_u32 v168, v2, 2, s0
	v_or_b32_e32 v2, 0x42, v100
	v_lshl_add_u32 v143, v3, 2, v11
	v_sub_u32_e32 v3, v2, v103
	v_cmp_gt_u32_e64 s[80:81], s1, v3
	v_lshl_add_u32 v169, v3, 2, s0
	v_or_b32_e32 v3, 0x43, v100
	v_lshl_add_u32 v144, v4, 2, v11
	v_sub_u32_e32 v4, v3, v103
	v_cmp_gt_u32_e64 s[82:83], s1, v4
	v_lshl_add_u32 v170, v4, 2, s0
	v_or_b32_e32 v4, 0x44, v100
	v_add_u32_e32 v0, v0, v9
	v_lshl_add_u32 v145, v5, 2, v11
	v_sub_u32_e32 v5, v4, v103
	v_cmp_gt_u32_e64 s[92:93], s1, v0
	v_lshl_add_u32 v175, v0, 2, s0
	v_add_u32_e32 v0, v1, v9
	v_cmp_gt_u32_e64 s[84:85], s1, v5
	v_lshl_add_u32 v171, v5, 2, s0
	v_or_b32_e32 v5, 0x45, v100
	v_cmp_gt_u32_e64 s[94:95], s1, v0
	v_lshl_add_u32 v182, v0, 2, s0
	v_add_u32_e32 v0, v2, v9
	v_writelane_b32 v249, s4, 33
	v_lshl_add_u32 v146, v6, 2, v11
	v_sub_u32_e32 v6, v5, v103
	v_cmp_gt_u32_e64 s[96:97], s1, v0
	v_lshl_add_u32 v183, v0, 2, s0
	v_add_u32_e32 v0, v3, v9
	v_writelane_b32 v249, s5, 34
	v_cmp_gt_u32_e64 s[86:87], s1, v6
	v_lshl_add_u32 v172, v6, 2, s0
	v_or_b32_e32 v6, 0x46, v100
	v_cmp_gt_u32_e64 s[4:5], s1, v0
	v_lshl_add_u32 v184, v0, 2, s0
	v_add_u32_e32 v0, v4, v9
	v_lshl_add_u32 v147, v7, 2, v11
	v_sub_u32_e32 v7, v6, v103
	v_cmp_gt_u32_e64 s[6:7], s1, v0
	v_lshl_add_u32 v185, v0, 2, s0
	v_add_u32_e32 v0, v5, v9
	v_cmp_gt_u32_e64 s[88:89], s1, v7
	v_lshl_add_u32 v173, v7, 2, s0
	v_or_b32_e32 v7, 0x47, v100
	v_cmp_gt_u32_e64 s[8:9], s1, v0
	v_lshl_add_u32 v186, v0, 2, s0
	v_add_u32_e32 v0, v6, v9
	v_lshl_add_u32 v148, v8, 2, v11
	v_sub_u32_e32 v8, v7, v103
	v_cmp_gt_u32_e64 s[10:11], s1, v0
	v_lshl_add_u32 v187, v0, 2, s0
	v_add_u32_e32 v0, v7, v9
	v_and_or_b32 v111, v176, 16, v211
	v_or_b32_e32 v113, 0x800000, v100
	v_ashrrev_i32_e32 v115, 7, v176
	v_lshl_add_u32 v101, v176, 2, s0
	v_lshlrev_b32_e32 v116, 5, v103
	v_cmp_gt_u32_e64 s[90:91], s1, v8
	v_lshl_add_u32 v174, v8, 2, s0
	v_cmp_gt_u32_e64 s[12:13], s1, v0
	v_lshl_add_u32 v188, v0, 2, s0
	v_lshl_or_b32 v189, v103, 4, v100
	v_readlane_b32 s0, v253, 27
	v_readlane_b32 s1, v253, 28
	s_branch .LBB0_100

.Lsc_reinit:
	v_readlane_b32 s2, v251, 55
	v_readlane_b32 s3, v251, 56
	v_mov_b32_e32 v0, v179
	s_andn2_b64 vcc, exec, s[2:3]
	s_cbranch_vccnz .LBB0_303
	v_readfirstlane_b32 s98, v179
	s_nop 3
	s_lshr_b32 s98, s98, 8
	s_cmp_eq_u32 s98, 0
	s_cbranch_scc1 .Lprio_293
	s_setprio 1
.Lprio_293:
	v_and_b32_e32 v2, 15, v0
	v_readlane_b32 s2, v251, 61
	v_lshlrev_b32_e32 v176, 2, v2
	v_readlane_b32 s3, v251, 62
	v_and_b32_e32 v6, 0x7f, v0
	v_and_b32_e32 v1, 63, v0
	v_lshl_add_u64 v[24:25], s[2:3], 0, v[176:177]
	v_readlane_b32 s2, v252, 1
	v_lshlrev_b32_e32 v176, 2, v6
	v_readlane_b32 s3, v252, 2
	v_lshlrev_b32_e32 v8, 1, v1
	v_mov_b32_e32 v9, v177
	v_lshl_add_u64 v[26:27], s[2:3], 0, v[176:177]
	v_readlane_b32 s2, v251, 63
	v_readlane_b32 s3, v252, 0
	v_bfe_u32 v3, v0, 4, 2
	v_ashrrev_i32_e32 v5, 6, v0
	v_ashrrev_i32_e32 v12, 7, v0
	v_lshl_add_u64 v[28:29], s[2:3], 0, v[8:9]
	v_readlane_b32 s2, v253, 44
	s_movk_i32 s14, 0x90
	v_lshlrev_b32_e32 v11, 2, v3
	v_lshlrev_b32_e32 v54, 4, v12
	v_lshl_add_u32 v56, v0, 2, s2
	v_mad_u32_u24 v9, v1, s14, 0
	v_add_u32_e32 v57, s2, v176
	s_movk_i32 s2, 0x80
	v_lshlrev_b32_e32 v1, 5, v5
	v_lshlrev_b32_e32 v3, 3, v3
	v_readlane_b32 s5, v253, 46
	v_and_b32_e32 v15, 48, v0
	v_cmp_gt_u32_e32 vcc, s2, v0
	v_add3_u32 v3, s5, v1, v3
	v_and_b32_e32 v8, 32, v1
	v_or_b32_e32 v1, v54, v2
	v_add_u32_e32 v10, 0, v15
	s_movk_i32 s2, 0x110
	v_lshlrev_b32_e32 v7, 4, v5
	v_readlane_b32 s4, v253, 45
	v_mad_u64_u32 v[30:31], s[2:3], v1, s2, v[10:11]
	v_and_b32_e32 v0, 0xffffffc0, v0
	v_or_b32_e32 v4, v11, v7
	v_or_b32_e32 v31, v11, v54
	v_add_u32_e32 v11, s4, v0
	v_or_b32_e32 v0, v7, v2
	v_mad_u64_u32 v[32:33], s[2:3], v0, s14, v[10:11]
	v_lshlrev_b32_e32 v0, 7, v1
	v_sub_u32_e32 v33, v30, v0
	v_or_b32_e32 v0, 1, v4
	v_ashrrev_i32_e32 v1, 31, v0
	v_lshlrev_b64 v[36:37], 10, v[0:1]
	v_or_b32_e32 v0, 2, v4
	v_ashrrev_i32_e32 v1, 31, v0
	v_lshlrev_b64 v[38:39], 10, v[0:1]
	v_or_b32_e32 v0, 3, v4
	v_ashrrev_i32_e32 v1, 31, v0
	s_movk_i32 s2, 0x880
	v_lshlrev_b64 v[40:41], 10, v[0:1]
	v_mul_lo_u32 v0, v12, s2
	v_or_b32_e32 v63, 2, v54
	v_or_b32_e32 v0, v0, v6
	s_movk_i32 s2, 0x88
	v_lshl_add_u32 v106, v0, 1, 0
	v_mad_u64_u32 v[0:1], s[2:3], v63, s2, v[6:7]
	v_or_b32_e32 v1, v8, v2
	v_add_u32_e32 v58, s4, v176
	v_lshlrev_b32_e32 v14, 5, v12
	v_add_u32_e32 v16, s5, v15
	v_cmp_lt_i32_e64 s[4:5], 0, v12
	v_cmp_lt_i32_e64 s[6:7], 1, v12
	v_cmp_lt_i32_e64 s[8:9], 2, v12
	v_cmp_lt_i32_e64 s[10:11], 3, v12
	v_mul_u32_u24_e32 v12, 0x88, v1
	v_lshlrev_b32_e32 v12, 1, v12
	v_readlane_b32 s2, v251, 59
	v_lshlrev_b32_e32 v55, 3, v5
	v_ashrrev_i32_e32 v5, 31, v4
	v_add_u32_e32 v114, v10, v12
	v_add_u32_e32 v115, v16, v12
	v_or_b32_e32 v12, 16, v1
	v_readlane_b32 s3, v251, 60
	v_mul_u32_u24_e32 v17, 0x88, v12
	v_lshlrev_b32_e32 v17, 1, v17
	v_lshl_add_u64 v[42:43], v[4:5], 2, s[2:3]
	v_readlane_b32 s2, v251, 57
	v_or_b32_e32 v118, 1, v31
	v_or_b32_e32 v119, 2, v31
	v_or_b32_e32 v120, 3, v31
	v_lshlrev_b32_e32 v176, 1, v6
	v_readlane_b32 s3, v251, 58
	v_mad_u32_u24 v13, v6, s14, 0
	v_or_b32_e32 v61, 1, v54
	v_or_b32_e32 v65, 3, v54
	v_or_b32_e32 v67, 4, v54
	v_or_b32_e32 v69, 5, v54
	v_or_b32_e32 v71, 6, v54
	v_or_b32_e32 v73, 7, v54
	v_or_b32_e32 v75, 8, v54
	v_or_b32_e32 v77, 9, v54
	v_or_b32_e32 v79, 10, v54
	v_or_b32_e32 v81, 11, v54
	v_or_b32_e32 v83, 12, v54
	v_or_b32_e32 v85, 13, v54
	v_or_b32_e32 v87, 14, v54
	v_or_b32_e32 v89, 15, v54
	v_or_b32_e32 v92, 1, v55
	v_or_b32_e32 v94, 2, v55
	v_or_b32_e32 v96, 3, v55
	v_or_b32_e32 v98, 4, v55
	v_or_b32_e32 v100, 5, v55
	v_or_b32_e32 v102, 6, v55
	v_or_b32_e32 v104, 7, v55
	v_lshl_add_u32 v107, v0, 1, 0
	v_mul_u32_u24_e32 v0, 0x110, v2
	v_add_u32_e32 v116, v10, v17
	v_add_u32_e32 v117, v16, v17
	v_lshl_add_u32 v16, v1, 1, 0
	v_cmp_gt_i32_e64 s[12:13], v1, v31
	v_mul_lo_u32 v17, v31, s14
	v_cmp_gt_i32_e64 s[14:15], v1, v118
	v_cmp_gt_i32_e64 s[16:17], v1, v119
	v_cmp_gt_i32_e64 s[18:19], v1, v120
	v_cmp_gt_i32_e64 s[20:21], v12, v31
	v_cmp_gt_i32_e64 s[22:23], v12, v118
	v_cmp_gt_i32_e64 s[24:25], v12, v119
	v_cmp_gt_i32_e64 s[38:39], v12, v120
	v_mul_u32_u24_e32 v18, 0x90, v2
	v_mul_u32_u24_e32 v1, 0x90, v1
	v_mul_u32_u24_e32 v12, 0x90, v12
	v_lshl_add_u64 v[44:45], s[2:3], 0, v[176:177]
	v_readlane_b32 s2, v253, 27
	v_lshlrev_b64 v[34:35], 10, v[4:5]
	v_sub_u32_e32 v59, 63, v31
	v_sub_u32_e32 v60, 63, v54
	v_sub_u32_e32 v62, 63, v61
	v_sub_u32_e32 v64, 63, v63
	v_sub_u32_e32 v66, 63, v65
	v_sub_u32_e32 v68, 63, v67
	v_sub_u32_e32 v70, 63, v69
	v_sub_u32_e32 v72, 63, v71
	v_sub_u32_e32 v74, 63, v73
	v_sub_u32_e32 v76, 63, v75
	v_sub_u32_e32 v78, 63, v77
	v_sub_u32_e32 v80, 63, v79
	v_sub_u32_e32 v82, 63, v81
	v_sub_u32_e32 v84, 63, v83
	v_sub_u32_e32 v86, 63, v85
	v_sub_u32_e32 v88, 63, v87
	v_sub_u32_e32 v90, 63, v89
	v_sub_u32_e32 v91, 63, v55
	v_sub_u32_e32 v93, 63, v92
	v_sub_u32_e32 v95, 63, v94
	v_sub_u32_e32 v97, 63, v96
	v_sub_u32_e32 v99, 63, v98
	v_sub_u32_e32 v101, 63, v100
	v_sub_u32_e32 v103, 63, v102
	v_sub_u32_e32 v105, 63, v104
	v_add_u32_e32 v108, 0x220, v107
	v_add_u32_e32 v109, 0x440, v107
	v_add_u32_e32 v110, 0x660, v107
	v_add_u32_e32 v111, 0x880, v107
	v_add_u32_e32 v112, 0xaa0, v107
	v_add_u32_e32 v113, 0xcc0, v107
	v_sub_u32_e32 v121, 63, v118
	v_sub_u32_e32 v122, 63, v119
	v_sub_u32_e32 v123, 63, v120
	v_lshlrev_b32_e32 v176, 2, v2
	v_lshlrev_b32_e32 v46, 2, v8
	v_add_u32_e32 v124, v9, v7
	v_add_u32_e32 v125, v13, v14
	v_add_u32_e32 v126, v3, v0
	v_add_u32_e32 v127, v16, v17
	v_add_u32_e32 v128, v11, v15
	v_add_u32_e32 v129, v10, v18
	v_add_u32_e32 v130, v10, v1
	v_add_u32_e32 v131, v10, v12
	v_readlane_b32 s3, v253, 28
	s_branch .LBB0_295

.LBB0_304:
	s_and_b64 vcc, exec, s[2:3]
	s_cbranch_vccz .LBB0_315
	v_readlane_b32 s2, v249, 56
	s_cmp_gt_i32 s2, 10
	s_mov_b64 s[2:3], -1
	s_cbranch_scc0 .LBB0_317
	v_readlane_b32 s2, v251, 55
	v_readlane_b32 s3, v251, 56
	v_mov_b32_e32 v0, v179
	s_andn2_b64 vcc, exec, s[2:3]
	s_cbranch_vccnz .LBB0_316
	v_readfirstlane_b32 s98, v179
	s_nop 3
	s_lshr_b32 s98, s98, 8
	s_cmp_eq_u32 s98, 0
	s_cbranch_scc1 .Lprio_307
	s_setprio 1
.Lprio_307:
	v_and_b32_e32 v4, 0x7f, v0
	v_readlane_b32 s2, v252, 1
	v_lshlrev_b32_e32 v176, 2, v4
	v_readlane_b32 s3, v252, 2
	v_and_b32_e32 v1, 63, v0
	v_lshlrev_b32_e32 v6, 1, v1
	v_lshl_add_u64 v[20:21], s[2:3], 0, v[176:177]
	v_readlane_b32 s2, v251, 63
	v_mov_b32_e32 v7, v177
	v_readlane_b32 s3, v252, 0
	v_ashrrev_i32_e32 v3, 6, v0
	v_and_b32_e32 v2, 15, v0
	v_lshl_add_u64 v[22:23], s[2:3], 0, v[6:7]
	v_readlane_b32 s3, v253, 44
	s_movk_i32 s2, 0x90
	v_lshlrev_b32_e32 v43, 3, v3
	v_lshl_add_u32 v44, v0, 2, s3
	v_mad_u32_u24 v7, v1, s2, 0
	v_lshlrev_b32_e32 v3, 4, v3
	v_add_u32_e32 v45, s3, v176
	v_readlane_b32 s3, v253, 45
	v_and_b32_e32 v1, 0xffffffc0, v0
	v_and_b32_e32 v13, 48, v0
	v_add_u32_e32 v12, s3, v1
	v_or_b32_e32 v1, v3, v2
	v_add_u32_e32 v6, 0, v13
	v_add_u32_e32 v46, s3, v176
	v_mad_u32_u24 v10, v4, s2, 0
	v_mad_u64_u32 v[24:25], s[2:3], v1, s2, v[6:7]
	v_lshrrev_b32_e32 v1, 2, v0
	v_readlane_b32 s2, v251, 59
	s_movk_i32 s4, 0x80
	v_and_or_b32 v8, v1, 12, v3
	v_ashrrev_i32_e32 v1, 31, v0
	v_readlane_b32 s3, v251, 60
	v_ashrrev_i32_e32 v5, 7, v0
	v_cmp_gt_u32_e32 vcc, s4, v0
	v_cmp_gt_i32_e64 s[4:5], s4, v0
	v_lshl_add_u64 v[26:27], v[0:1], 2, s[2:3]
	v_or_b32_e32 v0, 1, v8
	v_ashrrev_i32_e32 v1, 31, v0
	v_lshlrev_b64 v[30:31], 10, v[0:1]
	v_or_b32_e32 v0, 2, v8
	v_ashrrev_i32_e32 v1, 31, v0
	v_lshlrev_b32_e32 v42, 4, v5
	v_lshlrev_b64 v[32:33], 10, v[0:1]
	v_or_b32_e32 v0, 3, v8
	v_lshlrev_b32_e32 v11, 5, v5
	v_mul_u32_u24_e32 v14, 0x90, v2
	v_or_b32_e32 v47, 1, v42
	v_or_b32_e32 v49, 2, v42
	v_or_b32_e32 v51, 3, v42
	v_or_b32_e32 v53, 4, v42
	v_or_b32_e32 v55, 5, v42
	v_or_b32_e32 v57, 6, v42
	v_or_b32_e32 v59, 7, v42
	v_or_b32_e32 v61, 8, v42
	v_or_b32_e32 v63, 9, v42
	v_or_b32_e32 v65, 10, v42
	v_or_b32_e32 v67, 11, v42
	v_or_b32_e32 v69, 12, v42
	v_or_b32_e32 v71, 13, v42
	v_or_b32_e32 v73, 14, v42
	v_or_b32_e32 v75, 15, v42
	v_or_b32_e32 v78, 1, v43
	v_or_b32_e32 v80, 2, v43
	v_or_b32_e32 v82, 3, v43
	v_or_b32_e32 v84, 4, v43
	v_or_b32_e32 v86, 5, v43
	v_or_b32_e32 v88, 6, v43
	v_or_b32_e32 v90, 7, v43
	v_ashrrev_i32_e32 v9, 31, v8
	v_ashrrev_i32_e32 v1, 31, v0
	v_readlane_b32 s2, v253, 27
	v_sub_u32_e32 v25, 63, v42
	v_sub_u32_e32 v48, 63, v47
	v_sub_u32_e32 v50, 63, v49
	v_sub_u32_e32 v52, 63, v51
	v_sub_u32_e32 v54, 63, v53
	v_sub_u32_e32 v56, 63, v55
	v_sub_u32_e32 v58, 63, v57
	v_sub_u32_e32 v60, 63, v59
	v_sub_u32_e32 v62, 63, v61
	v_sub_u32_e32 v64, 63, v63
	v_sub_u32_e32 v66, 63, v65
	v_sub_u32_e32 v68, 63, v67
	v_sub_u32_e32 v70, 63, v69
	v_sub_u32_e32 v72, 63, v71
	v_sub_u32_e32 v74, 63, v73
	v_sub_u32_e32 v76, 63, v75
	v_sub_u32_e32 v77, 63, v43
	v_sub_u32_e32 v79, 63, v78
	v_sub_u32_e32 v81, 63, v80
	v_sub_u32_e32 v83, 63, v82
	v_sub_u32_e32 v85, 63, v84
	v_sub_u32_e32 v87, 63, v86
	v_sub_u32_e32 v89, 63, v88
	v_cmp_lt_i32_e64 s[6:7], 0, v5
	v_cmp_lt_i32_e64 s[8:9], 1, v5
	v_cmp_lt_i32_e64 s[10:11], 2, v5
	v_cmp_lt_i32_e64 s[12:13], 3, v5
	v_sub_u32_e32 v91, 63, v90
	v_lshlrev_b32_e32 v176, 1, v4
	v_lshlrev_b64 v[28:29], 10, v[8:9]
	v_add_u32_e32 v92, v7, v3
	v_add_u32_e32 v93, v10, v11
	v_add_u32_e32 v94, v6, v14
	v_lshlrev_b64 v[34:35], 10, v[0:1]
	v_add_u32_e32 v95, v12, v13
	v_lshlrev_b32_e32 v36, 2, v2
	s_mov_b32 s18, s2
	v_readlane_b32 s3, v253, 28
	s_branch .LBB0_309
